# P6 split 128/128 + prompt-attention items grouped one head per XCD (12 consecutive items per WG) for L2 reuse of K/V across branches and halos
# baseline (speedup 1.0000x reference)
; __device__ __forceinline__ void attn_mfma_phase(LAS unsigned char* lds, const bf16* QKVb, bf16* OPART, float2* ML, int tid, int wave, int lane) {
;     ...
;     if ((int)blockIdx.x < 1536) issue(blockIdx.x);
;     for (int item = blockIdx.x; item < 1536; item += gridDim.x) {
;         int h, b, r, bk; decode(item, h, b, r, bk);
;         const int d = 1 << (2 * b), L0 = bk * 256;
.LBB0_986:
	s_cmpk_ge_i32 s86, 128
	s_cbranch_scc1 .Lhl_a
	s_and_b32 s98, s86, 7
	s_mul_i32 s98, s98, 192
	s_lshr_b32 s86, s86, 3
	s_mul_i32 s86, s86, 12
	s_add_i32 s86, s86, s98
	s_add_i32 s98, s86, 12
	s_branch .Lhl_j
.Lhl_a:
	s_movk_i32 s86, 0x600
	s_movk_i32 s98, 0x600

; #define LAS __attribute__((address_space(3)))
; __device__ __forceinline__ void attn_mfma_phase(LAS unsigned char* lds, const bf16* QKVb, bf16* OPART, float2* ML, int tid, int wave, int lane) {
;     ...
;     for (int item = blockIdx.x; item < 1536; item += gridDim.x) {
;         int h, b, r, bk; decode(item, h, b, r, bk);
;         const int d = 1 << (2 * b), L0 = bk * 256;
; #pragma unroll
;         for (int c = 0; c < 6; ++c) { const int e = tid + NTHR * c, j = e >> 3, ch = e & 7;
;             *(LAS v4u*)(kimg + j * RSK + 16 * ch) = pk[c]; *(LAS v4u*)(vimg + j * RSV + 16 * ch) = pv[c]; }
;         const int l0 = L0 + 32 * wave;
;         const int tok_q = (l0 + i) * d + r;
;         const bf16* qp = QKVb + (size_t)tok_q * INW + C_QA + h * 64 + 8 * hh;
;         bf16x8 qf[4];
; #pragma unroll
;         for (int ks = 0; ks < 4; ++ks) qf[ks] = *(const bf16x8*)(qp + 16 * ks);
;         __syncthreads();
;         if (item + (int)gridDim.x < 1536) issue(item + gridDim.x);
.LBB0_1018:
	s_lshl_b32 s87, s84, 8
	s_add_i32 s87, s87, s2
	s_lshl_b32 s70, s1, 1
	v_or_b32_e32 v2, s87, v133
	v_lshlrev_b32_e32 v2, s70, v2
	v_readlane_b32 s70, v254, 55
	v_readlane_b32 s71, v254, 56
	v_add_u32_e32 v148, s33, v2
	s_lshl_b32 s94, s0, 6
	v_mov_b64_e32 v[2:3], s[70:71]
	v_mad_i64_i32 v[2:3], s[70:71], v148, s3, v[2:3]
	s_ashr_i32 s95, s94, 31
	v_lshl_add_u64 v[2:3], s[94:95], 1, v[2:3]
	v_lshl_add_u64 v[2:3], v[2:3], 0, v[142:143]
	global_load_dwordx4 v[114:117], v[2:3], off
	global_load_dwordx4 v[118:121], v[2:3], off offset:32
	global_load_dwordx4 v[122:125], v[2:3], off offset:64
	global_load_dwordx4 v[126:129], v[2:3], off offset:96
	s_movk_i32 s33, 1
	s_add_i32 s86, s86, s33
	s_cmp_ge_i32 s86, s98
	s_cselect_b64 s[72:73], -1, 0
	v_add_u32_e32 v2, v135, v155
	s_and_b64 vcc, exec, s[72:73]
	s_waitcnt vmcnt(5)
	ds_write_b128 v159, v[70:73]
	s_waitcnt vmcnt(4)
	ds_write_b128 v2, v[66:69] offset:55296
	ds_write_b128 v160, v[78:81]
	ds_write_b128 v161, v[74:77] offset:55296
	ds_write_b128 v159, v[86:89] offset:18432
	ds_write_b128 v168, v[82:85] offset:55296
	ds_write_b128 v169, v[94:97]
	ds_write_b128 v170, v[90:93] offset:55296
	ds_write_b128 v159, v[102:105] offset:36864
	ds_write_b128 v171, v[98:101] offset:55296
	ds_write_b128 v172, v[110:113]
	ds_write_b128 v173, v[106:109] offset:55296
	s_waitcnt lgkmcnt(0)
	s_barrier
	s_cbranch_vccnz .LBB0_1039
	s_mul_hi_i32 s33, s86, 0x2aaaaaab
	s_lshr_b32 s70, s33, 31
	s_ashr_i32 s96, s33, 5
	s_add_i32 s96, s96, s70
	s_mul_i32 s33, s96, 0xc0
	s_sub_i32 s70, s86, s33
	s_cmp_lt_i32 s70, 64
	s_mov_b32 s84, 0
	s_cbranch_scc1 .LBB0_1025
	s_cmpk_gt_u32 s70, 0x7f
	s_mov_b64 s[92:93], -1
	s_cbranch_scc0 .LBB0_1022
	s_add_i32 s33, s70, 0xffffff80
	s_lshr_b32 s84, s33, 2
	s_and_b32 s33, s70, 3
	s_mov_b64 s[92:93], 0
